# rowpass: hoist gout gain loads out of loop, drop artifact vmcnt waits
# baseline (speedup 1.0000x reference)
; __device__ __forceinline__ void rowpass(CArgs a, int gw, int NGW, int lane, bool init, const bf16_t* __restrict__ src, const float* __restrict__ gadd,
;                                         bool has_out, const float* __restrict__ gout, bf16_t* __restrict__ out) {
;     constexpr int RP = 4;
;     float* X = a->out;
;     for (int m0 = gw * RP; m0 < NTOK; m0 += NGW * RP) {
;         f32x4 v[RP][4]; u32x2 sv[RP][4];
; #pragma unroll
;         for (int q = 0; q < RP; ++q) { const int m = m0 + q;
;             const float* xin = init ? (m < HTOK ? a->in[0] + (size_t)m * DM : a->in[1] + (size_t)(m - HTOK) * DM) : X + (size_t)m * DM;
; #pragma unroll
;             for (int j = 0; j < 4; ++j) v[q][j] = *(const f32x4*)(xin + lane * 4 + 256 * j);
;             if (src) {
; #pragma unroll
;                 for (int j = 0; j < 4; ++j) sv[q][j] = *(const u32x2*)(src + (size_t)m * DM + lane * 4 + 256 * j);
;     ...
;             for (int j = 0; j < 4; ++j) { f32x4 g = (f32x4){1.f, 1.f, 1.f, 1.f}; if (gout) g = *(const f32x4*)(gout + lane * 4 + 256 * j);
.LBB0_231:
	v_writelane_b32 v254, s20, 59
	s_xor_b64 s[8:9], s[12:13], -1
	v_writelane_b32 v254, s8, 60
	s_xor_b64 s[2:3], s[2:3], -1
	s_ashr_i32 s6, s6, 6
	v_writelane_b32 v254, s9, 61
	v_writelane_b32 v254, s2, 62
	v_and_b32_e32 v167, 63, v209
	s_mov_b64 s[50:51], 0
	v_writelane_b32 v254, s3, 63
	s_xor_b64 s[2:3], s[34:35], -1
	v_writelane_b32 v255, s2, 0
	v_readlane_b32 s7, v254, 48
	s_mov_b64 s[12:13], 0
	v_writelane_b32 v255, s3, 1
	v_readlane_b32 s2, v252, 8
	s_add_i32 s48, s6, s2
	s_mov_b64 s[2:3], -1
	s_cmp_lt_i32 s7, 3
	s_cbranch_scc1 .LBB0_367
	v_readlane_b32 s2, v254, 48
	s_cmp_gt_i32 s2, 3
	s_cbranch_scc0 .LBB0_260
	s_cmp_gt_i32 s2, 6
	s_cbranch_scc0 .LBB0_261
	s_cmp_eq_u32 s2, 7
	s_mov_b64 s[12:13], -1
	s_cbranch_scc0 .LBB0_262
	s_cmpk_gt_i32 s48, 0x1fff
	s_cbranch_scc1 .LBB0_263
	s_lshl_b32 s12, s48, 2
	s_cmp_lg_u64 s[4:5], 0
	s_cselect_b64 s[34:35], -1, 0
	s_cmp_lg_u64 s[18:19], 0
	s_cselect_b64 s[44:45], -1, 0
	s_ashr_i32 s13, s12, 31
	s_load_dwordx2 s[2:3], s[42:43], 0xe0
	s_lshl_b64 s[8:9], s[12:13], 11
	s_add_u32 s46, s4, s8
	s_addc_u32 s47, s5, s9
	s_add_u32 s52, s92, s8
	s_addc_u32 s53, s93, s9
	s_lshl_b64 s[4:5], s[12:13], 12
	s_waitcnt lgkmcnt(0)
	s_add_u32 s2, s2, s4
	s_waitcnt vmcnt(0)
	v_lshlrev_b32_e32 v2, 4, v167
	v_mov_b32_e32 v3, v1
	s_addc_u32 s3, s3, s5
	v_lshl_add_u64 v[82:83], s[16:17], 0, v[2:3]
	v_lshl_add_u64 v[84:85], s[18:19], 0, v[2:3]
	v_lshl_add_u64 v[2:3], s[2:3], 0, v[2:3]
	s_mov_b64 s[2:3], 0x3c00
	v_lshlrev_b32_e32 v0, 3, v167
	v_lshl_add_u64 v[86:87], v[2:3], 0, s[2:3]
	v_cndmask_b32_e64 v142, 0, 1, s[34:35]
	v_mov_b32_e32 v236, 1.0
	v_mov_b32_e32 v237, 1.0
	v_mov_b32_e32 v238, 1.0
	v_mov_b32_e32 v239, 1.0
	v_mov_b32_e32 v240, 1.0
	v_mov_b32_e32 v241, 1.0
	v_mov_b32_e32 v242, 1.0
	v_mov_b32_e32 v243, 1.0
	v_mov_b32_e32 v244, 1.0
	v_mov_b32_e32 v245, 1.0
	v_mov_b32_e32 v246, 1.0
	v_mov_b32_e32 v247, 1.0
	v_mov_b32_e32 v248, 1.0
	v_mov_b32_e32 v249, 1.0
	v_mov_b32_e32 v250, 1.0
	v_mov_b32_e32 v251, 1.0
	s_andn2_b64 vcc, exec, s[44:45]
	s_cbranch_vccnz .Lrp_nogout
	global_load_dwordx4 v[236:239], v[84:85], off
	global_load_dwordx4 v[240:243], v[84:85], off offset:1024
	global_load_dwordx4 v[244:247], v[84:85], off offset:2048
	global_load_dwordx4 v[248:251], v[84:85], off offset:3072
	s_waitcnt vmcnt(0)

; __device__ __forceinline__ unsigned pk2(float lo, float hi) { f32x2_t v = {lo, hi}; bf16x2_t b = __builtin_convertvector(v, bf16x2_t); return __builtin_bit_cast(unsigned, b); }
; __device__ __forceinline__ void rowpass(CArgs a, int gw, int NGW, int lane, bool init, const bf16_t* __restrict__ src, const float* __restrict__ gadd,
;                                         bool has_out, const float* __restrict__ gout, bf16_t* __restrict__ out) {
;     ...
;             for (int j = 0; j < 4; ++j) { f32x4 g = (f32x4){1.f, 1.f, 1.f, 1.f}; if (gout) g = *(const f32x4*)(gout + lane * 4 + 256 * j);
; #pragma unroll
;                 for (int q = 0; q < RP; ++q) { const float r2 = rsqrtf(s2[q] * (1.f / DM) + EPS);
;                     u32x2 w; w.x = pk2(v[q][j][0] * r2 * g[0], v[q][j][1] * r2 * g[1]); w.y = pk2(v[q][j][2] * r2 * g[2], v[q][j][3] * r2 * g[3]);
;                     *(u32x2*)(out + (size_t)(m0 + q) * DM + lane * 4 + 256 * j) = w; } }
.LBB0_237:
	v_pk_mul_f32 v[2:3], v[2:3], v[72:73]
	v_pk_mul_f32 v[4:5], v[4:5], v[72:73]
	v_pk_mul_f32 v[2:3], v[2:3], v[34:35]
	v_pk_mul_f32 v[4:5], v[4:5], v[36:37]
	v_cvt_pk_bf16_f32 v2, v2, v3
	v_cvt_pk_bf16_f32 v3, v4, v5
	global_store_dwordx2 v[52:53], v[2:3], off offset:1536
	v_pk_mul_f32 v[2:3], v[6:7], v[74:75]
	v_pk_mul_f32 v[4:5], v[8:9], v[74:75]
	v_pk_mul_f32 v[2:3], v[2:3], v[34:35]
	v_pk_mul_f32 v[4:5], v[4:5], v[36:37]
	v_cvt_pk_bf16_f32 v2, v2, v3
	v_cvt_pk_bf16_f32 v3, v4, v5
	global_store_dwordx2 v[52:53], v[2:3], off offset:3584
	v_pk_mul_f32 v[2:3], v[10:11], v[54:55]
	v_pk_mul_f32 v[4:5], v[12:13], v[54:55]
	v_pk_mul_f32 v[2:3], v[2:3], v[34:35]
	v_pk_mul_f32 v[4:5], v[4:5], v[36:37]
	v_cvt_pk_bf16_f32 v2, v2, v3
	v_cvt_pk_bf16_f32 v3, v4, v5
	global_store_dwordx2 v[50:51], v[2:3], off offset:1536
	v_pk_mul_f32 v[2:3], v[14:15], v[56:57]
	v_pk_mul_f32 v[4:5], v[16:17], v[56:57]
	v_pk_mul_f32 v[2:3], v[2:3], v[34:35]
	v_pk_mul_f32 v[4:5], v[4:5], v[36:37]
	v_cvt_pk_bf16_f32 v2, v2, v3
	v_cvt_pk_bf16_f32 v3, v4, v5
	global_store_dwordx2 v[50:51], v[2:3], off offset:3584

; __device__ __forceinline__ void rowpass(CArgs a, int gw, int NGW, int lane, bool init, const bf16_t* __restrict__ src, const float* __restrict__ gadd,
;                                         bool has_out, const float* __restrict__ gout, bf16_t* __restrict__ out) {
;     ...
;     for (int m0 = gw * RP; m0 < NTOK; m0 += NGW * RP) {
;         f32x4 v[RP][4]; u32x2 sv[RP][4];
; #pragma unroll
;         for (int q = 0; q < RP; ++q) { const int m = m0 + q;
;             const float* xin = init ? (m < HTOK ? a->in[0] + (size_t)m * DM : a->in[1] + (size_t)(m - HTOK) * DM) : X + (size_t)m * DM;
; #pragma unroll
;             for (int j = 0; j < 4; ++j) v[q][j] = *(const f32x4*)(xin + lane * 4 + 256 * j);
;             if (src) {
; #pragma unroll
;                 for (int j = 0; j < 4; ++j) sv[q][j] = *(const u32x2*)(src + (size_t)m * DM + lane * 4 + 256 * j);
;             } }
.LBB0_239:
	v_add_co_u32_e32 v2, vcc, 0xffffd000, v86
	v_cmp_ne_u32_e64 s[38:39], 1, v142
	s_nop 0
	v_addc_co_u32_e32 v3, vcc, -1, v87, vcc
	global_load_dwordx4 v[50:53], v[2:3], off offset:-3072
	global_load_dwordx4 v[34:37], v[2:3], off offset:-2048
	global_load_dwordx4 v[18:21], v[2:3], off offset:-1024
	s_nop 0
	global_load_dwordx4 v[2:5], v[2:3], off
	s_andn2_b64 vcc, exec, s[34:35]
	v_lshl_add_u64 v[66:67], s[46:47], 0, v[0:1]
	s_cbranch_vccnz .LBB0_241
	global_load_dwordx2 v[118:119], v[66:67], off
	global_load_dwordx2 v[116:117], v[66:67], off offset:512
	global_load_dwordx2 v[114:115], v[66:67], off offset:1024
	global_load_dwordx2 v[112:113], v[66:67], off offset:1536
.LBB0_241:
	v_add_co_u32_e32 v6, vcc, 0xffffe000, v86
	s_nop 1
	v_addc_co_u32_e32 v7, vcc, -1, v87, vcc
	global_load_dwordx4 v[54:57], v[6:7], off offset:-3072
	global_load_dwordx4 v[38:41], v[6:7], off offset:-2048
	global_load_dwordx4 v[22:25], v[6:7], off offset:-1024
	s_nop 0
	global_load_dwordx4 v[6:9], v[6:7], off
	s_and_b64 vcc, exec, s[38:39]
	s_cbranch_vccnz .LBB0_243
	global_load_dwordx2 v[102:103], v[66:67], off offset:2048
	global_load_dwordx2 v[100:101], v[66:67], off offset:2560
	global_load_dwordx2 v[98:99], v[66:67], off offset:3072
	global_load_dwordx2 v[96:97], v[66:67], off offset:3584
.LBB0_243:
	v_add_co_u32_e32 v10, vcc, 0xfffff000, v86
	s_nop 1
	v_addc_co_u32_e32 v11, vcc, -1, v87, vcc
	global_load_dwordx4 v[58:61], v[10:11], off offset:-3072
	global_load_dwordx4 v[42:45], v[10:11], off offset:-2048
	global_load_dwordx4 v[26:29], v[10:11], off offset:-1024
	s_nop 0
	global_load_dwordx4 v[10:13], v[86:87], off offset:-4096
	s_and_b64 vcc, exec, s[38:39]
	s_cbranch_vccnz .LBB0_245
	v_add_co_u32_e32 v14, vcc, 0x1000, v66
	s_nop 1
	v_addc_co_u32_e32 v15, vcc, 0, v67, vcc
	global_load_dwordx2 v[110:111], v[14:15], off
	global_load_dwordx2 v[108:109], v[14:15], off offset:512
	global_load_dwordx2 v[106:107], v[14:15], off offset:1024
	global_load_dwordx2 v[104:105], v[14:15], off offset:1536

; __device__ __forceinline__ void rowpass(CArgs a, int gw, int NGW, int lane, bool init, const bf16_t* __restrict__ src, const float* __restrict__ gadd,
;                                         bool has_out, const float* __restrict__ gout, bf16_t* __restrict__ out) {
;     ...
;         if (has_out) {
;             float s2[RP];
; #pragma unroll
;             for (int q = 0; q < RP; ++q) { s2[q] = 0.f;
; #pragma unroll
;                 for (int j = 0; j < 4; ++j) s2[q] += (v[q][j][0] * v[q][j][0] + v[q][j][1] * v[q][j][1]) + (v[q][j][2] * v[q][j][2] + v[q][j][3] * v[q][j][3]); }
; #pragma unroll
;             for (int o = 1; o < 64; o <<= 1) {
; #pragma unroll
;                 for (int q = 0; q < RP; ++q) s2[q] += __shfl_xor(s2[q], o); }
; #pragma unroll
;             for (int j = 0; j < 4; ++j) { f32x4 g = (f32x4){1.f, 1.f, 1.f, 1.f}; if (gout) g = *(const f32x4*)(gout + lane * 4 + 256 * j);
.LBB0_251:
	s_andn2_b64 vcc, exec, s[26:27]
	s_cbranch_vccnz .LBB0_238
	v_mov_b32_e32 v68, v55
	v_mov_b32_e32 v69, v51
	v_mov_b32_e32 v66, v54
	v_mov_b32_e32 v67, v50
	v_pk_mul_f32 v[68:69], v[68:69], v[68:69]
	v_mov_b32_e32 v70, v57
	v_mov_b32_e32 v71, v53
	v_pk_fma_f32 v[66:67], v[66:67], v[66:67], v[68:69]
	v_mov_b32_e32 v68, v56
	v_mov_b32_e32 v69, v52
	v_pk_mul_f32 v[70:71], v[70:71], v[70:71]
	v_mov_b32_e32 v122, v63
	v_mov_b32_e32 v123, v59
	v_pk_fma_f32 v[68:69], v[68:69], v[68:69], v[70:71]
	v_mov_b32_e32 v70, v39
	v_mov_b32_e32 v71, v35
	v_mov_b32_e32 v120, v62
	v_mov_b32_e32 v121, v58
	v_pk_mul_f32 v[122:123], v[122:123], v[122:123]
	v_mov_b32_e32 v124, v65
	v_mov_b32_e32 v125, v61
	v_pk_add_f32 v[66:67], v[66:67], v[68:69]
	v_mov_b32_e32 v68, v38
	v_mov_b32_e32 v69, v34
	v_pk_mul_f32 v[70:71], v[70:71], v[70:71]
	v_mov_b32_e32 v72, v41
	v_mov_b32_e32 v73, v37
	v_pk_fma_f32 v[120:121], v[120:121], v[120:121], v[122:123]
	v_mov_b32_e32 v122, v64
	v_mov_b32_e32 v123, v60
	v_pk_mul_f32 v[124:125], v[124:125], v[124:125]
	v_pk_fma_f32 v[68:69], v[68:69], v[68:69], v[70:71]
	v_mov_b32_e32 v70, v40
	v_mov_b32_e32 v71, v36
	v_pk_mul_f32 v[72:73], v[72:73], v[72:73]
	v_pk_fma_f32 v[122:123], v[122:123], v[122:123], v[124:125]
	v_mov_b32_e32 v124, v47
	v_mov_b32_e32 v125, v43
	v_pk_fma_f32 v[70:71], v[70:71], v[70:71], v[72:73]
	v_mov_b32_e32 v72, v23
	v_mov_b32_e32 v73, v19
	v_pk_add_f32 v[120:121], v[120:121], v[122:123]
	v_mov_b32_e32 v122, v46
	v_mov_b32_e32 v123, v42
	v_pk_mul_f32 v[124:125], v[124:125], v[124:125]
	v_mov_b32_e32 v126, v49
	v_mov_b32_e32 v127, v45
	v_pk_add_f32 v[68:69], v[68:69], v[70:71]
	v_mov_b32_e32 v70, v22
	v_mov_b32_e32 v71, v18
	v_pk_mul_f32 v[72:73], v[72:73], v[72:73]
	v_mov_b32_e32 v74, v25
	v_mov_b32_e32 v75, v21
	v_pk_fma_f32 v[122:123], v[122:123], v[122:123], v[124:125]
	v_mov_b32_e32 v124, v48
	v_mov_b32_e32 v125, v44
	v_pk_mul_f32 v[126:127], v[126:127], v[126:127]
	v_pk_fma_f32 v[70:71], v[70:71], v[70:71], v[72:73]
	v_mov_b32_e32 v72, v24
	v_mov_b32_e32 v73, v20
	v_pk_mul_f32 v[74:75], v[74:75], v[74:75]
	v_pk_fma_f32 v[124:125], v[124:125], v[124:125], v[126:127]
	v_mov_b32_e32 v126, v31
	v_mov_b32_e32 v127, v27
	v_pk_fma_f32 v[72:73], v[72:73], v[72:73], v[74:75]
	v_mov_b32_e32 v76, v7
	v_mov_b32_e32 v77, v3
	v_mov_b32_e32 v80, v9
	v_mov_b32_e32 v81, v5
	v_pk_add_f32 v[122:123], v[122:123], v[124:125]
	v_mov_b32_e32 v124, v30
	v_mov_b32_e32 v125, v26
	v_pk_mul_f32 v[126:127], v[126:127], v[126:127]
	v_mov_b32_e32 v128, v33
	v_mov_b32_e32 v129, v29
	v_mov_b32_e32 v74, v6
	v_mov_b32_e32 v75, v2
	v_pk_mul_f32 v[76:77], v[76:77], v[76:77]
	v_mov_b32_e32 v78, v8
	v_mov_b32_e32 v79, v4
	v_pk_mul_f32 v[80:81], v[80:81], v[80:81]
	v_pk_fma_f32 v[124:125], v[124:125], v[124:125], v[126:127]
	v_mov_b32_e32 v126, v32
	v_mov_b32_e32 v127, v28
	v_pk_mul_f32 v[128:129], v[128:129], v[128:129]
	v_pk_add_f32 v[66:67], v[68:69], v[66:67]
	v_pk_add_f32 v[68:69], v[70:71], v[72:73]
	v_pk_fma_f32 v[126:127], v[126:127], v[126:127], v[128:129]
	v_mov_b32_e32 v130, v15
	v_mov_b32_e32 v131, v11
	v_mov_b32_e32 v134, v17
	v_mov_b32_e32 v135, v13
	v_and_b32_e32 v136, 64, v203
	v_pk_add_f32 v[66:67], v[68:69], v[66:67]
	v_pk_fma_f32 v[68:69], v[74:75], v[74:75], v[76:77]
	v_pk_fma_f32 v[70:71], v[78:79], v[78:79], v[80:81]
	v_mov_b32_e32 v128, v14
	v_mov_b32_e32 v129, v10
	v_pk_mul_f32 v[130:131], v[130:131], v[130:131]
	v_mov_b32_e32 v132, v16
	v_mov_b32_e32 v133, v12
	v_pk_mul_f32 v[134:135], v[134:135], v[134:135]
	v_add_u32_e32 v136, 64, v136
	v_xor_b32_e32 v137, 1, v203
	v_pk_add_f32 v[68:69], v[68:69], v[70:71]
	v_pk_add_f32 v[70:71], v[122:123], v[120:121]
	v_pk_add_f32 v[72:73], v[124:125], v[126:127]
	v_cmp_lt_i32_e32 vcc, v137, v136
	v_pk_add_f32 v[70:71], v[72:73], v[70:71]
	v_pk_fma_f32 v[72:73], v[128:129], v[128:129], v[130:131]
	v_pk_fma_f32 v[74:75], v[132:133], v[132:133], v[134:135]
	v_cndmask_b32_e32 v137, v203, v137, vcc
	v_pk_add_f32 v[72:73], v[72:73], v[74:75]
	v_lshlrev_b32_e32 v137, 2, v137
	v_pk_add_f32 v[66:67], v[68:69], v[66:67]
	v_pk_add_f32 v[70:71], v[72:73], v[70:71]
	ds_bpermute_b32 v69, v137, v67
	ds_bpermute_b32 v68, v137, v66
	ds_bpermute_b32 v73, v137, v71
	ds_bpermute_b32 v72, v137, v70
	v_xor_b32_e32 v138, 2, v203
	v_cmp_lt_i32_e32 vcc, v138, v136
	s_waitcnt lgkmcnt(2)
	v_pk_add_f32 v[66:67], v[66:67], v[68:69]
	v_xor_b32_e32 v139, 4, v203
	v_cndmask_b32_e32 v138, v203, v138, vcc
	v_lshlrev_b32_e32 v138, 2, v138
	s_waitcnt lgkmcnt(0)
	v_pk_add_f32 v[70:71], v[70:71], v[72:73]
	ds_bpermute_b32 v69, v138, v67
	ds_bpermute_b32 v68, v138, v66
	ds_bpermute_b32 v73, v138, v71
	ds_bpermute_b32 v72, v138, v70
	v_cmp_lt_i32_e32 vcc, v139, v136
	v_xor_b32_e32 v140, 8, v203
	s_waitcnt lgkmcnt(2)
	v_pk_add_f32 v[66:67], v[66:67], v[68:69]
	v_cndmask_b32_e32 v139, v203, v139, vcc
	v_lshlrev_b32_e32 v139, 2, v139
	s_waitcnt lgkmcnt(0)
	v_pk_add_f32 v[70:71], v[70:71], v[72:73]
	ds_bpermute_b32 v69, v139, v67
	ds_bpermute_b32 v68, v139, v66
	ds_bpermute_b32 v73, v139, v71
	ds_bpermute_b32 v72, v139, v70
	v_cmp_lt_i32_e32 vcc, v140, v136
	v_xor_b32_e32 v141, 16, v203
	s_waitcnt lgkmcnt(2)
	v_pk_add_f32 v[66:67], v[66:67], v[68:69]
	v_cndmask_b32_e32 v140, v203, v140, vcc
	v_lshlrev_b32_e32 v140, 2, v140
	s_waitcnt lgkmcnt(0)
	v_pk_add_f32 v[70:71], v[70:71], v[72:73]
	ds_bpermute_b32 v69, v140, v67
	ds_bpermute_b32 v68, v140, v66
	ds_bpermute_b32 v73, v140, v71
	ds_bpermute_b32 v72, v140, v70
	v_cmp_lt_i32_e32 vcc, v141, v136
	v_xor_b32_e32 v75, 32, v203
	s_waitcnt lgkmcnt(2)
	v_pk_add_f32 v[66:67], v[66:67], v[68:69]
	v_cndmask_b32_e32 v74, v203, v141, vcc
	v_lshlrev_b32_e32 v74, 2, v74
	s_waitcnt lgkmcnt(0)
	v_pk_add_f32 v[70:71], v[70:71], v[72:73]
	ds_bpermute_b32 v69, v74, v67
	ds_bpermute_b32 v68, v74, v66
	ds_bpermute_b32 v73, v74, v71
	ds_bpermute_b32 v72, v74, v70
	v_cmp_lt_i32_e32 vcc, v75, v136
	s_waitcnt lgkmcnt(2)
	v_pk_add_f32 v[76:77], v[66:67], v[68:69]
	v_cndmask_b32_e32 v75, v203, v75, vcc
	v_lshlrev_b32_e32 v74, 2, v75
	s_waitcnt lgkmcnt(0)
	v_pk_add_f32 v[72:73], v[70:71], v[72:73]
	ds_bpermute_b32 v79, v74, v77
	ds_bpermute_b32 v78, v74, v76
	ds_bpermute_b32 v75, v74, v73
	ds_bpermute_b32 v74, v74, v72
	v_cndmask_b32_e64 v67, 0, 1, s[44:45]
	v_mov_b32_e32 v66, 1.0
	v_cmp_ne_u32_e64 s[38:39], 1, v67
	s_andn2_b64 vcc, exec, s[44:45]
	v_mov_b32_e32 v68, 1.0
	v_mov_b32_e32 v69, 1.0
	v_mov_b32_e32 v70, 1.0
	v_mov_b32_e32 v71, 1.0
	s_cbranch_vccnz .LBB0_254
	v_mov_b64_e32 v[68:69], v[236:237]
	v_mov_b64_e32 v[70:71], v[238:239]
; __device__ __forceinline__ unsigned pk2(float lo, float hi) { f32x2_t v = {lo, hi}; bf16x2_t b = __builtin_convertvector(v, bf16x2_t); return __builtin_bit_cast(unsigned, b); }
; __device__ __forceinline__ void rowpass(CArgs a, int gw, int NGW, int lane, bool init, const bf16_t* __restrict__ src, const float* __restrict__ gadd,
;                                         bool has_out, const float* __restrict__ gout, bf16_t* __restrict__ out) {
;     ...
;             for (int j = 0; j < 4; ++j) { f32x4 g = (f32x4){1.f, 1.f, 1.f, 1.f}; if (gout) g = *(const f32x4*)(gout + lane * 4 + 256 * j);
; #pragma unroll
;                 for (int q = 0; q < RP; ++q) { const float r2 = rsqrtf(s2[q] * (1.f / DM) + EPS);
;                     u32x2 w; w.x = pk2(v[q][j][0] * r2 * g[0], v[q][j][1] * r2 * g[1]); w.y = pk2(v[q][j][2] * r2 * g[2], v[q][j][3] * r2 * g[3]);
;                     *(u32x2*)(out + (size_t)(m0 + q) * DM + lane * 4 + 256 * j) = w; } }
.LBB0_254:
	s_mov_b32 s2, 0x358637bd
	s_waitcnt lgkmcnt(2)
	v_pk_add_f32 v[76:77], v[76:77], v[78:79]
	v_mov_b64_e32 v[78:79], s[2:3]
	s_mov_b32 s4, 0x3a800000
	v_pk_fma_f32 v[76:77], v[76:77], s[4:5], v[78:79] op_sel_hi:[1,0,0]
	s_waitcnt lgkmcnt(0)
	v_pk_add_f32 v[80:81], v[72:73], v[74:75]
	v_mul_f32_e32 v67, 0x4b800000, v77
	v_cmp_gt_f32_e32 vcc, s55, v77
	v_lshl_add_u64 v[74:75], s[52:53], 0, v[0:1]
	s_mov_b32 s2, 0x3800000
	v_cndmask_b32_e32 v67, v77, v67, vcc
	v_rsq_f32_e32 v67, v67
	s_nop 0
	v_mul_f32_e32 v72, 0x45800000, v67
	v_cndmask_b32_e32 v72, v67, v72, vcc
	v_pk_mul_f32 v[50:51], v[50:51], v[72:73] op_sel_hi:[1,0]
	v_pk_mul_f32 v[50:51], v[50:51], v[68:69]
	s_nop 0
	v_cvt_pk_bf16_f32 v120, v50, v51
	v_pk_mul_f32 v[50:51], v[52:53], v[72:73] op_sel_hi:[1,0]
	v_add_co_u32_e32 v52, vcc, s2, v74
	v_pk_mul_f32 v[50:51], v[50:51], v[70:71]
	s_nop 0
	v_addc_co_u32_e32 v53, vcc, 0, v75, vcc
	v_cvt_pk_bf16_f32 v121, v50, v51
	v_mul_f32_e32 v50, 0x4b800000, v76
	v_cmp_gt_f32_e32 vcc, s55, v76
	s_mov_b32 s2, 0x3801000
	s_nop 0
	v_cndmask_b32_e32 v50, v76, v50, vcc
	v_rsq_f32_e32 v67, v50
	v_add_co_u32_e64 v50, s[40:41], s2, v74
	v_pk_fma_f32 v[76:77], v[80:81], s[4:5], v[78:79] op_sel_hi:[1,0,0]
	v_mul_f32_e32 v73, 0x45800000, v67
	v_cndmask_b32_e32 v74, v67, v73, vcc
	v_pk_mul_f32 v[54:55], v[54:55], v[74:75] op_sel_hi:[1,0]
	v_cmp_gt_f32_e32 vcc, s55, v77
	v_pk_mul_f32 v[54:55], v[54:55], v[68:69]
	v_pk_mul_f32 v[56:57], v[56:57], v[74:75] op_sel_hi:[1,0]
	v_cvt_pk_bf16_f32 v54, v54, v55
	v_mul_f32_e32 v55, 0x4b800000, v77
	v_cndmask_b32_e32 v55, v77, v55, vcc
	v_rsq_f32_e32 v67, v55
	v_pk_mul_f32 v[56:57], v[56:57], v[70:71]
	v_addc_co_u32_e64 v51, s[40:41], 0, v75, s[40:41]
	v_cvt_pk_bf16_f32 v55, v56, v57
	global_store_dwordx2 v[52:53], v[54:55], off offset:2048
	v_mul_f32_e32 v54, 0x45800000, v67
	v_cndmask_b32_e32 v54, v67, v54, vcc
	v_pk_mul_f32 v[56:57], v[58:59], v[54:55] op_sel_hi:[1,0]
	v_pk_mul_f32 v[58:59], v[60:61], v[54:55] op_sel_hi:[1,0]
	v_mul_f32_e32 v55, 0x4b800000, v76
	v_cmp_gt_f32_e32 vcc, s55, v76
	v_pk_mul_f32 v[56:57], v[56:57], v[68:69]
	v_pk_mul_f32 v[58:59], v[58:59], v[70:71]
	v_cndmask_b32_e32 v55, v76, v55, vcc
	v_rsq_f32_e32 v55, v55
	v_cvt_pk_bf16_f32 v56, v56, v57
	v_cvt_pk_bf16_f32 v57, v58, v59
	global_store_dwordx2 v[50:51], v[56:57], off
	v_mul_f32_e32 v56, 0x45800000, v55
	v_cndmask_b32_e32 v56, v55, v56, vcc
	v_pk_mul_f32 v[58:59], v[62:63], v[56:57] op_sel_hi:[1,0]
	v_pk_mul_f32 v[60:61], v[64:65], v[56:57] op_sel_hi:[1,0]
	v_pk_mul_f32 v[58:59], v[58:59], v[68:69]
	v_pk_mul_f32 v[60:61], v[60:61], v[70:71]
	v_cvt_pk_bf16_f32 v58, v58, v59
	v_cvt_pk_bf16_f32 v59, v60, v61
	s_and_b64 vcc, exec, s[38:39]
	v_mov_b32_e32 v67, 1.0
	v_mov_b32_e32 v68, 1.0
	v_mov_b32_e32 v69, 1.0
	global_store_dwordx2 v[50:51], v[120:121], off offset:-4096
	global_store_dwordx2 v[50:51], v[58:59], off offset:2048
	s_cbranch_vccnz .LBB0_256
	v_mov_b64_e32 v[66:67], v[240:241]
	v_mov_b64_e32 v[68:69], v[242:243]
.LBB0_256:
	v_mov_b32_e32 v73, v72
	v_pk_mul_f32 v[34:35], v[34:35], v[72:73]
	v_pk_mul_f32 v[36:37], v[36:37], v[72:73]
	v_pk_mul_f32 v[34:35], v[34:35], v[66:67]
	v_pk_mul_f32 v[36:37], v[36:37], v[68:69]
	v_mov_b32_e32 v75, v74
	v_cvt_pk_bf16_f32 v34, v34, v35
	v_cvt_pk_bf16_f32 v35, v36, v37
	global_store_dwordx2 v[52:53], v[34:35], off offset:512
	v_pk_mul_f32 v[34:35], v[38:39], v[74:75]
	v_pk_mul_f32 v[36:37], v[40:41], v[74:75]
	v_pk_mul_f32 v[34:35], v[34:35], v[66:67]
	v_pk_mul_f32 v[36:37], v[36:37], v[68:69]
	v_mov_b32_e32 v55, v54
	v_cvt_pk_bf16_f32 v34, v34, v35
	v_cvt_pk_bf16_f32 v35, v36, v37
	global_store_dwordx2 v[52:53], v[34:35], off offset:2560
	v_pk_mul_f32 v[34:35], v[42:43], v[54:55]
	v_pk_mul_f32 v[36:37], v[44:45], v[54:55]
	v_pk_mul_f32 v[34:35], v[34:35], v[66:67]
	v_pk_mul_f32 v[36:37], v[36:37], v[68:69]
	v_mov_b32_e32 v57, v56
	v_cvt_pk_bf16_f32 v34, v34, v35
	v_cvt_pk_bf16_f32 v35, v36, v37
	global_store_dwordx2 v[50:51], v[34:35], off offset:512
	v_pk_mul_f32 v[34:35], v[46:47], v[56:57]
	v_pk_mul_f32 v[36:37], v[48:49], v[56:57]
	v_pk_mul_f32 v[34:35], v[34:35], v[66:67]
	v_pk_mul_f32 v[36:37], v[36:37], v[68:69]
	v_cvt_pk_bf16_f32 v34, v34, v35
	v_cvt_pk_bf16_f32 v35, v36, v37
	global_store_dwordx2 v[50:51], v[34:35], off offset:2560
	v_mov_b32_e32 v34, 1.0
	s_and_b64 vcc, exec, s[38:39]
	v_mov_b32_e32 v36, 1.0
	v_mov_b32_e32 v37, 1.0
	v_mov_b32_e32 v38, 1.0
	v_mov_b32_e32 v39, 1.0
	s_cbranch_vccnz .LBB0_258
	v_mov_b64_e32 v[36:37], v[244:245]
	v_mov_b64_e32 v[38:39], v[246:247]
.LBB0_258:
	v_pk_mul_f32 v[18:19], v[18:19], v[72:73]
	v_pk_mul_f32 v[20:21], v[20:21], v[72:73]
	v_pk_mul_f32 v[18:19], v[18:19], v[36:37]
	v_pk_mul_f32 v[20:21], v[20:21], v[38:39]
	v_cvt_pk_bf16_f32 v18, v18, v19
	v_cvt_pk_bf16_f32 v19, v20, v21
	global_store_dwordx2 v[52:53], v[18:19], off offset:1024
	v_pk_mul_f32 v[18:19], v[22:23], v[74:75]
	v_pk_mul_f32 v[20:21], v[24:25], v[74:75]
	v_pk_mul_f32 v[18:19], v[18:19], v[36:37]
	v_pk_mul_f32 v[20:21], v[20:21], v[38:39]
	v_cvt_pk_bf16_f32 v18, v18, v19
	v_cvt_pk_bf16_f32 v19, v20, v21
	global_store_dwordx2 v[52:53], v[18:19], off offset:3072
	v_pk_mul_f32 v[18:19], v[26:27], v[54:55]
	v_pk_mul_f32 v[20:21], v[28:29], v[54:55]
	v_pk_mul_f32 v[18:19], v[18:19], v[36:37]
	v_pk_mul_f32 v[20:21], v[20:21], v[38:39]
	v_cvt_pk_bf16_f32 v18, v18, v19
	v_cvt_pk_bf16_f32 v19, v20, v21
	global_store_dwordx2 v[50:51], v[18:19], off offset:1024
	v_pk_mul_f32 v[18:19], v[30:31], v[56:57]
	v_pk_mul_f32 v[20:21], v[32:33], v[56:57]
	v_pk_mul_f32 v[18:19], v[18:19], v[36:37]
	v_pk_mul_f32 v[20:21], v[20:21], v[38:39]
	v_cvt_pk_bf16_f32 v18, v18, v19
	v_cvt_pk_bf16_f32 v19, v20, v21
	s_and_b64 vcc, exec, s[38:39]
	v_mov_b32_e32 v35, 1.0
	v_mov_b32_e32 v36, 1.0
	v_mov_b32_e32 v37, 1.0
	global_store_dwordx2 v[50:51], v[18:19], off offset:3072
	s_cbranch_vccnz .LBB0_237
	v_mov_b64_e32 v[34:35], v[248:249]
	v_mov_b64_e32 v[36:37], v[250:251]
	s_branch .LBB0_237
